# NSA top-k inner loop rewritten branch-free (exec never changes) + paired importance LDS read-modify-writes, on v19
# baseline (speedup 1.0000x reference)
; template <int CTRL> __device__ __forceinline__ unsigned dppu(unsigned x) { return (unsigned)__builtin_amdgcn_mov_dpp((int)x, CTRL, 0xf, 0xf, true); }
; __device__ __forceinline__ unsigned wave_max_u32(unsigned x) {
;     x = max(x, dppu<0xB1>(x)); x = max(x, dppu<0x4E>(x)); x = max(x, dppu<0x141>(x)); x = max(x, dppu<0x140>(x));
;     auto s = __builtin_amdgcn_permlane16_swap(x, x, false, false); x = max((unsigned)s[0], (unsigned)s[1]);
;     auto t = __builtin_amdgcn_permlane32_swap(x, x, false, false); return max((unsigned)t[0], (unsigned)t[1]);
; }
; __device__ __forceinline__ void nsa_block(LAS unsigned char* lds, int b, int g, int t0b, int tid) {
;     ...
;             unsigned sb = 0u;
;             for (int it = 0; it < nsel; ++it) {
;                 const unsigned best = wave_max_u32(max(max(k0, k1), max(k2, k3)));
;                 const int bi = 255 - (int)(best & 0xffu);
;                 if ((bi & 63) == lane) { const int ii = bi >> 6; sb |= 1u << ii; if (ii == 0) k0 = 0u; else if (ii == 1) k1 = 0u; else if (ii == 2) k2 = 0u; else k3 = 0u; }
;             }
.Ltopk_it:
	v_max_u32_e32 v64, v61, v60
	v_max3_u32 v64, v59, v58, v64
	s_nop 1
	v_max_u32_dpp v64, v64, v64 quad_perm:[1,0,3,2] row_mask:0xf bank_mask:0xf bound_ctrl:1
	s_nop 1
	v_max_u32_dpp v64, v64, v64 quad_perm:[2,3,0,1] row_mask:0xf bank_mask:0xf bound_ctrl:1
	s_nop 1
	v_max_u32_dpp v64, v64, v64 row_half_mirror row_mask:0xf bank_mask:0xf bound_ctrl:1
	s_nop 1
	v_max_u32_dpp v64, v64, v64 row_mirror row_mask:0xf bank_mask:0xf bound_ctrl:1
	v_mov_b32_e32 v65, v64
	s_nop 1
	v_permlane16_swap_b32_e32 v64, v65
	v_max_u32_e32 v64, v64, v65
	v_mov_b32_e32 v65, v64
	s_nop 1
	v_permlane32_swap_b32_e32 v64, v65
	v_max_u32_e32 v64, v64, v65
	v_cmp_eq_u32_e64 s[60:61], v59, v64
	v_cmp_eq_u32_e64 s[62:63], v58, v64
	v_cmp_eq_u32_e64 s[64:65], v61, v64
	v_cmp_eq_u32_e64 s[66:67], v60, v64
	v_cndmask_b32_e64 v59, v59, 0, s[60:61]
	v_cndmask_b32_e64 v65, 0, 1, s[60:61]
	v_cndmask_b32_e64 v58, v58, 0, s[62:63]
	v_cndmask_b32_e64 v66, 0, 2, s[62:63]
	v_or3_b32 v62, v62, v65, v66
	v_cndmask_b32_e64 v61, v61, 0, s[64:65]
	v_cndmask_b32_e64 v65, 0, 4, s[64:65]
	v_cndmask_b32_e64 v60, v60, 0, s[66:67]
	v_cndmask_b32_e64 v66, 0, 8, s[66:67]
	v_or3_b32 v62, v62, v65, v66
	v_add_u32_e32 v63, -1, v63
	v_cmp_eq_u32_e32 vcc, 0, v63
	s_cbranch_vccz .Ltopk_it
